# dilated attention: bijective unit-index remap so a workgroup handles consecutive query blocks of one sequence and neighbours share an XCD (L2 reuse of the 128 overlapping K/V rows)
# baseline (speedup 1.0000x reference)
.LBB0_481:
	s_add_u32 s2, s74, s0
	s_addc_u32 s3, s75, s1
	global_load_dwordx4 v[2:5], v0, s[2:3] offset:16
	global_load_dwordx4 v[10:13], v0, s[2:3]
	s_add_u32 s2, s76, s0
	s_addc_u32 s3, s77, s1
	global_load_dwordx4 v[14:17], v0, s[2:3]
	global_load_dwordx4 v[18:21], v0, s[2:3] offset:16
	s_add_u32 s0, s0, 32
	s_addc_u32 s1, s1, 0
	s_cmpk_lg_i32 s0, 0x100
	s_waitcnt vmcnt(2)
	v_max3_f32 v1, v8, |v10|, |v11|
	v_max3_f32 v1, v1, |v12|, |v13|
	s_waitcnt vmcnt(1)
	v_max3_f32 v6, v9, |v14|, |v15|
	v_max3_f32 v1, v1, |v2|, |v3|
	v_max3_f32 v2, v6, |v16|, |v17|
	v_max3_f32 v8, v1, |v4|, |v5|
	s_waitcnt vmcnt(0)
	v_max3_f32 v1, v2, |v18|, |v19|
	v_max3_f32 v9, v1, |v20|, |v21|
	s_cbranch_scc1 .LBB0_481
	v_readlane_b32 s0, v254, 36
	v_readlane_b32 s1, v254, 37
	s_lshr_b32 s98, s0, 8
	s_and_b32 s99, s0, 0xff
	s_and_b32 s101, s99, 7
	s_lshr_b32 s99, s99, 3
	s_cmp_lt_u32 s98, 2
	s_cbranch_scc1 .Ldg_p0_a
	s_cmp_lt_u32 s98, 4
	s_cbranch_scc1 .Ldg_p1_a
	s_lshl_b32 s101, s101, 6
	s_lshl_b32 s99, s99, 1
	s_add_i32 s101, s101, s99
	s_add_i32 s101, s101, s98
	s_add_i32 s101, s101, -4
	s_mul_i32 s0, s101, 3
	s_add_i32 s0, s0, 2
	s_branch .Ldg_done_a
.Ldg_p1_a:
	s_lshl_b32 s101, s101, 4
	s_lshr_b32 s0, s99, 1
	s_add_i32 s101, s101, s0
	s_and_b32 s99, s99, 1
	s_lshl_b32 s99, s99, 1
	s_add_i32 s99, s99, s98
	s_add_i32 s99, s99, -2
	s_lshr_b32 s0, s101, 2
	s_lshl_b32 s0, s0, 4
	s_lshl_b32 s99, s99, 2
	s_or_b32 s0, s0, s99
	s_and_b32 s101, s101, 3
	s_or_b32 s0, s0, s101
	s_mul_i32 s0, s0, 3
	s_add_i32 s0, s0, 1
	s_branch .Ldg_done_a
.Ldg_p0_a:
	s_lshl_b32 s101, s101, 2
	s_lshr_b32 s0, s99, 3
	s_add_i32 s101, s101, s0
	s_and_b32 s99, s99, 7
	s_lshl_b32 s99, s99, 1
	s_add_i32 s99, s99, s98
	s_lshl_b32 s101, s101, 4
	s_or_b32 s0, s101, s99
	s_mul_i32 s0, s0, 3
.Ldg_done_a:
	s_mov_b32 s2, s0
	s_mul_hi_i32 s0, s0, 0x55555556
	s_lshr_b32 s1, s0, 31
	s_add_i32 s0, s0, s1
	s_mul_i32 s1, s0, 3
	s_sub_i32 s76, s2, s1
	s_ashr_i32 s94, s0, 7
	s_bfe_u32 s92, s0, 0x30004
	s_and_b32 s0, s0, 15
	s_lshl_b32 s8, s76, 1
	s_lshr_b32 s93, s0, s8
	s_lshl_b32 s1, -1, s8
	s_lshl_b32 s14, s93, 8
	s_ashr_i32 s95, s94, 31
	v_lshlrev_b32_e32 v0, 3, v226
	s_andn2_b32 s77, s0, s1
	s_lshl_b64 s[0:1], s[94:95], 12
	s_add_i32 s15, s14, 0xffffff80
	v_and_b32_e32 v0, 56, v0
	v_mov_b32_e32 v96, 0
	s_mov_b32 s9, 0
	s_cmp_eq_u32 s93, 0
	v_lshlrev_b32_e32 v180, 1, v0
	s_cbranch_scc1 .LBB0_484
	v_lshrrev_b32_e32 v0, 3, v226
	v_or_b32_e32 v0, s15, v0
	v_mov_b32_e32 v1, v96
	v_lshlrev_b64 v[0:1], s8, v[0:1]
	s_or_b32 s2, s0, s77
	s_mov_b32 s3, s1
	v_lshl_add_u64 v[0:1], s[2:3], 0, v[0:1]
	s_movk_i32 s4, 0x1800
	v_mov_b64_e32 v[2:3], s[78:79]
	v_mad_u64_u32 v[2:3], s[2:3], v0, s4, v[2:3]
	v_mov_b32_e32 v0, v3
	v_mad_u64_u32 v[0:1], s[2:3], v1, s4, v[0:1]
	v_mov_b32_e32 v3, v0
	s_lshl_b32 s2, s92, 7
	s_mov_b32 s3, s9
	v_lshl_add_u64 v[0:1], v[2:3], 0, s[2:3]
	v_mov_b32_e32 v181, v96
	v_lshl_add_u64 v[0:1], v[0:1], 0, v[180:181]
	v_add_co_u32_e32 v0, vcc, 0x1000, v0
	s_nop 1
	v_addc_co_u32_e32 v1, vcc, 0, v1, vcc
	global_load_dwordx4 v[96:99], v[0:1], off
	global_load_dwordx4 v[100:103], v[0:1], off offset:1024
	s_branch .LBB0_485

.LBB0_491:
	s_mov_b32 s0, s15
	s_add_i32 s15, s15, s20
	s_cmpk_gt_i32 s15, 0x5ff
	s_cselect_b64 s[2:3], -1, 0
	s_cmpk_lt_i32 s15, 0x600
	s_cselect_b32 s0, s15, s0
	s_lshr_b32 s98, s0, 8
	s_and_b32 s99, s0, 0xff
	s_and_b32 s101, s99, 7
	s_lshr_b32 s99, s99, 3
	s_cmp_lt_u32 s98, 2
	s_cbranch_scc1 .Ldg_p0_b
	s_cmp_lt_u32 s98, 4
	s_cbranch_scc1 .Ldg_p1_b
	s_lshl_b32 s101, s101, 6
	s_lshl_b32 s99, s99, 1
	s_add_i32 s101, s101, s99
	s_add_i32 s101, s101, s98
	s_add_i32 s101, s101, -4
	s_mul_i32 s0, s101, 3
	s_add_i32 s0, s0, 2
	s_branch .Ldg_done_b

.Ldg_done_b:
	s_mul_hi_i32 s1, s0, 0x55555556
	s_lshr_b32 s6, s1, 31
	s_add_i32 s1, s1, s6
	s_mul_i32 s6, s1, 3
	ds_write_b128 v214, v[96:99]
	ds_write_b128 v215, v[100:103] offset:55296
	ds_write_b128 v216, v[108:111]
	ds_write_b128 v217, v[112:115] offset:55296
	ds_write_b128 v214, v[116:119] offset:18432
	ds_write_b128 v218, v[120:123] offset:55296
	ds_write_b128 v219, v[124:127]
	ds_write_b128 v220, v[128:131] offset:55296
	ds_write_b128 v214, v[132:135] offset:36864
	ds_write_b128 v221, v[136:139] offset:55296
	ds_write_b128 v222, v[144:147]
	ds_write_b128 v223, v[140:143] offset:55296
	s_sub_i32 s16, s0, s6
	s_waitcnt lgkmcnt(0)
	s_barrier
	s_lshl_b32 s70, s16, 1
	s_ashr_i32 s0, s1, 7
	s_bfe_u32 s17, s1, 0x30004
	s_and_b32 s1, s1, 15
	s_lshl_b32 s6, -1, s70
	s_andn2_b32 s18, s1, s6
	s_lshr_b32 s19, s1, s70
	s_and_b64 vcc, exec, s[2:3]
	s_cbranch_vccnz .LBB0_500
	s_lshl_b32 s95, s19, 8
	s_ashr_i32 s1, s0, 31
	s_lshl_b64 s[6:7], s[0:1], 12
	s_add_i32 s1, s95, 0xffffff80
	s_cmp_eq_u32 s19, 0
	s_cbranch_scc1 .LBB0_494
	v_or_b32_e32 v16, s1, v189
	v_mov_b32_e32 v17, v104
	v_lshlrev_b64 v[16:17], s70, v[16:17]
	s_or_b32 s74, s6, s18
	s_mov_b32 s75, s7
	v_lshl_add_u64 v[16:17], s[74:75], 0, v[16:17]
	v_mov_b64_e32 v[18:19], s[78:79]
	v_mad_u64_u32 v[18:19], s[74:75], v16, s12, v[18:19]
	v_mov_b32_e32 v16, v19
	v_mad_u64_u32 v[16:17], s[74:75], v17, s12, v[16:17]
	v_mov_b32_e32 v19, v16
	s_lshl_b32 s74, s17, 7
	s_mov_b32 s75, s71
	v_lshl_add_u64 v[16:17], v[18:19], 0, s[74:75]
	v_mov_b32_e32 v181, v104
	v_lshl_add_u64 v[16:17], v[16:17], 0, v[180:181]
	v_add_co_u32_e32 v16, vcc, 0x1000, v16
	s_nop 1
	v_addc_co_u32_e32 v17, vcc, 0, v17, vcc
	global_load_dwordx4 v[96:99], v[16:17], off
	global_load_dwordx4 v[100:103], v[16:17], off offset:1024
	s_branch .LBB0_495
